# adds E13b: GEMM units no longer clear accumulators (peeled first K-iteration uses C=0), stacked on E1,E4-E9,E11,E12
# speedup vs baseline: 1.0122x; 1.0065x over previous
.LBB0_216:
	s_ashr_i32 s59, s58, 31
	s_lshl_b64 s[10:11], s[58:59], 19
	s_add_u32 s50, s78, s10
	s_addc_u32 s51, s79, s11
	s_and_b64 s[10:11], s[38:39], exec
	s_cselect_b32 s12, s51, s3
	s_cselect_b32 s13, s50, s2
	s_ashr_i32 s53, s52, 31
	s_lshl_b64 s[10:11], s[52:53], 19
	s_add_u32 s60, s72, s10
	s_addc_u32 s61, s73, s11
	s_and_b64 s[10:11], s[38:39], exec
	s_cselect_b32 s14, s61, s9
	s_cselect_b32 s15, s60, s8
	s_ashr_i32 s5, s4, 31
	s_lshl_b64 s[10:11], s[4:5], 14
	s_add_u32 s2, s2, 0x40080
	s_addc_u32 s3, s3, 0
	v_lshl_add_u64 v[128:129], v[176:177], 0, s[10:11]
	s_mov_b64 s[10:11], 0x400
	s_add_u32 s5, s8, 0x100
	v_lshl_add_u64 v[130:131], v[128:129], 0, s[10:11]
	s_addc_u32 s16, s9, 0
	s_mov_b32 s17, -2
	s_mov_b64 s[8:9], 0
	s_add_u32 s18, s2, 0xfffc0080
	s_addc_u32 s19, s3, -1
	s_and_b64 s[10:11], s[8:9], exec
	s_cselect_b32 s11, s12, s19
	s_cselect_b32 s10, s13, s18
	s_add_i32 s18, 0, 0x10000
	s_and_b64 s[8:9], s[8:9], exec
	s_cselect_b32 s9, s14, s16
	s_cselect_b32 s8, s15, s5
	s_add_i32 s20, 0, 0x14000
	s_waitcnt vmcnt(0)
	v_add_u32_e32 v144, s18, v217
	v_add_u32_e32 v160, s20, v217
	ds_read_b128 v[132:135], v144
	ds_read_b128 v[136:139], v144 offset:1024
	ds_read_b128 v[140:143], v144 offset:2048
	ds_read_b128 v[144:147], v144 offset:3072
	ds_read_b128 v[148:151], v160
	ds_read_b128 v[152:155], v160 offset:1024
	ds_read_b128 v[156:159], v160 offset:2048
	ds_read_b128 v[160:163], v160 offset:3072
	v_lshl_add_u64 v[168:169], s[2:3], 0, v[178:179]
	s_add_i32 m0, s7, 0xc000
	ds_read_b128 v[164:167], v218
	ds_read_b128 v[182:185], v218 offset:1024
	ds_read_b128 v[186:189], v218 offset:2048
	ds_read_b128 v[204:207], v218 offset:3072
	ds_read_b128 v[208:211], v218 offset:4096
	ds_read_b128 v[220:223], v218 offset:5120
	ds_read_b128 v[224:227], v218 offset:6144
	ds_read_b128 v[242:245], v218 offset:7168
	global_load_lds_dwordx4 v[168:169], off
	v_lshl_add_u64 v[168:169], s[2:3], 0, v[180:181]
	s_add_i32 m0, s7, 0xe000
	s_nop 0
	global_load_lds_dwordx4 v[168:169], off
	s_waitcnt vmcnt(8)
	s_waitcnt lgkmcnt(0)
	s_barrier
	s_setprio 1
	s_waitcnt lgkmcnt(0)
	v_mfma_f32_16x16x32_bf16 v[124:127], v[132:135], v[164:167], 0
	v_mfma_f32_16x16x32_bf16 v[120:123], v[140:143], v[164:167], 0
	v_mfma_f32_16x16x32_bf16 v[108:111], v[132:135], v[186:189], 0
	v_mfma_f32_16x16x32_bf16 v[104:107], v[140:143], v[186:189], 0
	v_mfma_f32_16x16x32_bf16 v[92:95], v[132:135], v[208:211], 0
	v_mfma_f32_16x16x32_bf16 v[88:91], v[140:143], v[208:211], 0
	v_mfma_f32_16x16x32_bf16 v[76:79], v[132:135], v[224:227], 0
	v_mfma_f32_16x16x32_bf16 v[72:75], v[140:143], v[224:227], 0
	v_mfma_f32_16x16x32_bf16 v[124:127], v[136:139], v[182:185], v[124:127]
	v_mfma_f32_16x16x32_bf16 v[120:123], v[144:147], v[182:185], v[120:123]
	v_mfma_f32_16x16x32_bf16 v[108:111], v[136:139], v[204:207], v[108:111]
	v_mfma_f32_16x16x32_bf16 v[104:107], v[144:147], v[204:207], v[104:107]
	v_mfma_f32_16x16x32_bf16 v[92:95], v[136:139], v[220:223], v[92:95]
	v_mfma_f32_16x16x32_bf16 v[88:91], v[144:147], v[220:223], v[88:91]
	v_mfma_f32_16x16x32_bf16 v[76:79], v[136:139], v[242:245], v[76:79]
	v_mfma_f32_16x16x32_bf16 v[72:75], v[144:147], v[242:245], v[72:75]
	s_setprio 0
	s_setprio 1
	v_mfma_f32_16x16x32_bf16 v[116:119], v[148:151], v[164:167], 0
	v_mfma_f32_16x16x32_bf16 v[112:115], v[156:159], v[164:167], 0
	v_mfma_f32_16x16x32_bf16 v[100:103], v[148:151], v[186:189], 0
	v_mfma_f32_16x16x32_bf16 v[96:99], v[156:159], v[186:189], 0
	v_mfma_f32_16x16x32_bf16 v[84:87], v[148:151], v[208:211], 0
	v_mfma_f32_16x16x32_bf16 v[80:83], v[156:159], v[208:211], 0
	v_mfma_f32_16x16x32_bf16 v[68:71], v[148:151], v[224:227], 0
	v_mfma_f32_16x16x32_bf16 v[64:67], v[156:159], v[224:227], 0
	v_mfma_f32_16x16x32_bf16 v[116:119], v[152:155], v[182:185], v[116:119]
	v_mfma_f32_16x16x32_bf16 v[112:115], v[160:163], v[182:185], v[112:115]
	v_mfma_f32_16x16x32_bf16 v[100:103], v[152:155], v[204:207], v[100:103]
	v_mfma_f32_16x16x32_bf16 v[96:99], v[160:163], v[204:207], v[96:99]
	v_mfma_f32_16x16x32_bf16 v[84:87], v[152:155], v[220:223], v[84:87]
	v_mfma_f32_16x16x32_bf16 v[80:83], v[160:163], v[220:223], v[80:83]
	v_mfma_f32_16x16x32_bf16 v[68:71], v[152:155], v[242:245], v[68:71]
	v_mfma_f32_16x16x32_bf16 v[64:67], v[160:163], v[242:245], v[64:67]
	s_setprio 0
	s_barrier
	s_add_i32 s18, s18, s29
	v_lshl_add_u64 v[168:169], s[8:9], 0, v[192:193]
	s_mov_b32 m0, s18
	ds_read_b128 v[164:167], v218 offset:16384
	ds_read_b128 v[182:185], v218 offset:17408
	ds_read_b128 v[186:189], v218 offset:18432
	ds_read_b128 v[204:207], v218 offset:19456
	ds_read_b128 v[208:211], v218 offset:20480
	ds_read_b128 v[220:223], v218 offset:21504
	ds_read_b128 v[224:227], v218 offset:22528
	ds_read_b128 v[242:245], v218 offset:23552
	global_load_lds_dwordx4 v[168:169], off
	s_add_i32 m0, s18, 0x2000
	s_add_u32 s18, s8, 0x40000
	v_lshl_add_u64 v[190:191], s[8:9], 0, v[174:175]
	s_addc_u32 s19, s9, 0
	s_add_i32 s20, s20, s29
	global_load_lds_dwordx4 v[190:191], off
	v_lshl_add_u64 v[194:195], s[18:19], 0, v[192:193]
	s_mov_b32 m0, s20
	v_lshl_add_u64 v[196:197], s[10:11], 0, v[172:173]
	global_load_lds_dwordx4 v[194:195], off
	v_lshl_add_u64 v[194:195], s[18:19], 0, v[174:175]
	s_add_i32 m0, s20, 0x2000
	s_nop 0
	global_load_lds_dwordx4 v[194:195], off
	v_lshl_add_u64 v[194:195], s[10:11], 0, v[170:171]
	s_mov_b32 m0, s7
	s_nop 0
	global_load_lds_dwordx4 v[194:195], off
	s_mov_b32 m0, s34
	s_nop 0
	global_load_lds_dwordx4 v[196:197], off
	s_waitcnt vmcnt(8)
	s_waitcnt lgkmcnt(0)
	s_barrier
	s_setprio 1
	s_waitcnt lgkmcnt(0)
	v_mfma_f32_16x16x32_bf16 v[60:63], v[132:135], v[164:167], 0
	v_mfma_f32_16x16x32_bf16 v[56:59], v[140:143], v[164:167], 0
	v_mfma_f32_16x16x32_bf16 v[44:47], v[132:135], v[186:189], 0
	v_mfma_f32_16x16x32_bf16 v[40:43], v[140:143], v[186:189], 0
	v_mfma_f32_16x16x32_bf16 v[28:31], v[132:135], v[208:211], 0
	v_mfma_f32_16x16x32_bf16 v[24:27], v[140:143], v[208:211], 0
	v_mfma_f32_16x16x32_bf16 v[12:15], v[132:135], v[224:227], 0
	v_mfma_f32_16x16x32_bf16 v[8:11], v[140:143], v[224:227], 0
	v_mfma_f32_16x16x32_bf16 v[60:63], v[136:139], v[182:185], v[60:63]
	v_mfma_f32_16x16x32_bf16 v[56:59], v[144:147], v[182:185], v[56:59]
	v_mfma_f32_16x16x32_bf16 v[44:47], v[136:139], v[204:207], v[44:47]
	v_mfma_f32_16x16x32_bf16 v[40:43], v[144:147], v[204:207], v[40:43]
	v_mfma_f32_16x16x32_bf16 v[28:31], v[136:139], v[220:223], v[28:31]
	v_mfma_f32_16x16x32_bf16 v[24:27], v[144:147], v[220:223], v[24:27]
	v_mfma_f32_16x16x32_bf16 v[12:15], v[136:139], v[242:245], v[12:15]
	v_mfma_f32_16x16x32_bf16 v[8:11], v[144:147], v[242:245], v[8:11]
	s_setprio 0
	s_setprio 1
	v_mfma_f32_16x16x32_bf16 v[52:55], v[148:151], v[164:167], 0
	v_mfma_f32_16x16x32_bf16 v[48:51], v[156:159], v[164:167], 0
	v_mfma_f32_16x16x32_bf16 v[36:39], v[148:151], v[186:189], 0
	v_mfma_f32_16x16x32_bf16 v[32:35], v[156:159], v[186:189], 0
	v_mfma_f32_16x16x32_bf16 v[20:23], v[148:151], v[208:211], 0
	v_mfma_f32_16x16x32_bf16 v[16:19], v[156:159], v[208:211], 0
	v_mfma_f32_16x16x32_bf16 v[4:7], v[148:151], v[224:227], 0
	v_mfma_f32_16x16x32_bf16 v[0:3], v[156:159], v[224:227], 0
	v_mfma_f32_16x16x32_bf16 v[52:55], v[152:155], v[182:185], v[52:55]
	v_mfma_f32_16x16x32_bf16 v[48:51], v[160:163], v[182:185], v[48:51]
	v_mfma_f32_16x16x32_bf16 v[36:39], v[152:155], v[204:207], v[36:39]
	v_mfma_f32_16x16x32_bf16 v[32:35], v[160:163], v[204:207], v[32:35]
	v_mfma_f32_16x16x32_bf16 v[20:23], v[152:155], v[220:223], v[20:23]
	v_mfma_f32_16x16x32_bf16 v[16:19], v[160:163], v[220:223], v[16:19]
	v_mfma_f32_16x16x32_bf16 v[4:7], v[152:155], v[242:245], v[4:7]
	v_mfma_f32_16x16x32_bf16 v[0:3], v[160:163], v[242:245], v[0:3]
	s_setprio 0
	s_barrier
	s_add_i32 s18, 0, 0x18000
	s_add_i32 s19, 0, 0x1c000
	v_add_u32_e32 v144, s18, v217
	v_add_u32_e32 v160, s19, v217
	ds_read_b128 v[132:135], v144
	ds_read_b128 v[136:139], v144 offset:1024
	ds_read_b128 v[140:143], v144 offset:2048
	ds_read_b128 v[144:147], v144 offset:3072
	ds_read_b128 v[148:151], v160
	ds_read_b128 v[152:155], v160 offset:1024
	ds_read_b128 v[156:159], v160 offset:2048
	ds_read_b128 v[160:163], v160 offset:3072
	s_add_u32 s10, s10, 0x40000
	s_addc_u32 s11, s11, 0
	s_mov_b32 m0, s35
	v_lshl_add_u64 v[198:199], s[10:11], 0, v[170:171]
	ds_read_b128 v[164:167], v218 offset:32768
	ds_read_b128 v[182:185], v218 offset:33792
	ds_read_b128 v[186:189], v218 offset:34816
	ds_read_b128 v[204:207], v218 offset:35840
	ds_read_b128 v[208:211], v218 offset:36864
	ds_read_b128 v[220:223], v218 offset:37888
	ds_read_b128 v[224:227], v218 offset:38912
	ds_read_b128 v[242:245], v218 offset:39936
	global_load_lds_dwordx4 v[198:199], off
	v_lshl_add_u64 v[198:199], s[10:11], 0, v[172:173]
	s_mov_b32 m0, s84
	s_nop 0
	global_load_lds_dwordx4 v[198:199], off
	s_waitcnt vmcnt(8)
	s_waitcnt lgkmcnt(0)
	s_barrier
	s_setprio 1
	s_waitcnt lgkmcnt(0)
	v_mfma_f32_16x16x32_bf16 v[124:127], v[132:135], v[164:167], v[124:127]
	v_mfma_f32_16x16x32_bf16 v[120:123], v[140:143], v[164:167], v[120:123]
	v_mfma_f32_16x16x32_bf16 v[108:111], v[132:135], v[186:189], v[108:111]
	v_mfma_f32_16x16x32_bf16 v[104:107], v[140:143], v[186:189], v[104:107]
	v_mfma_f32_16x16x32_bf16 v[92:95], v[132:135], v[208:211], v[92:95]
	v_mfma_f32_16x16x32_bf16 v[88:91], v[140:143], v[208:211], v[88:91]
	v_mfma_f32_16x16x32_bf16 v[76:79], v[132:135], v[224:227], v[76:79]
	v_mfma_f32_16x16x32_bf16 v[72:75], v[140:143], v[224:227], v[72:75]
	v_mfma_f32_16x16x32_bf16 v[124:127], v[136:139], v[182:185], v[124:127]
	v_mfma_f32_16x16x32_bf16 v[120:123], v[144:147], v[182:185], v[120:123]
	v_mfma_f32_16x16x32_bf16 v[108:111], v[136:139], v[204:207], v[108:111]
	v_mfma_f32_16x16x32_bf16 v[104:107], v[144:147], v[204:207], v[104:107]
	v_mfma_f32_16x16x32_bf16 v[92:95], v[136:139], v[220:223], v[92:95]
	v_mfma_f32_16x16x32_bf16 v[88:91], v[144:147], v[220:223], v[88:91]
	v_mfma_f32_16x16x32_bf16 v[76:79], v[136:139], v[242:245], v[76:79]
	v_mfma_f32_16x16x32_bf16 v[72:75], v[144:147], v[242:245], v[72:75]
	s_setprio 0
	s_setprio 1
	v_mfma_f32_16x16x32_bf16 v[116:119], v[148:151], v[164:167], v[116:119]
	v_mfma_f32_16x16x32_bf16 v[112:115], v[156:159], v[164:167], v[112:115]
	v_mfma_f32_16x16x32_bf16 v[100:103], v[148:151], v[186:189], v[100:103]
	v_mfma_f32_16x16x32_bf16 v[96:99], v[156:159], v[186:189], v[96:99]
	v_mfma_f32_16x16x32_bf16 v[84:87], v[148:151], v[208:211], v[84:87]
	v_mfma_f32_16x16x32_bf16 v[80:83], v[156:159], v[208:211], v[80:83]
	v_mfma_f32_16x16x32_bf16 v[68:71], v[148:151], v[224:227], v[68:71]
	v_mfma_f32_16x16x32_bf16 v[64:67], v[156:159], v[224:227], v[64:67]
	v_mfma_f32_16x16x32_bf16 v[116:119], v[152:155], v[182:185], v[116:119]
	v_mfma_f32_16x16x32_bf16 v[112:115], v[160:163], v[182:185], v[112:115]
	v_mfma_f32_16x16x32_bf16 v[100:103], v[152:155], v[204:207], v[100:103]
	v_mfma_f32_16x16x32_bf16 v[96:99], v[160:163], v[204:207], v[96:99]
	v_mfma_f32_16x16x32_bf16 v[84:87], v[152:155], v[220:223], v[84:87]
	v_mfma_f32_16x16x32_bf16 v[80:83], v[160:163], v[220:223], v[80:83]
	v_mfma_f32_16x16x32_bf16 v[68:71], v[152:155], v[242:245], v[68:71]
	v_mfma_f32_16x16x32_bf16 v[64:67], v[160:163], v[242:245], v[64:67]
	s_setprio 0
	s_barrier
	s_add_i32 s10, s18, s29
	v_lshl_add_u64 v[168:169], v[168:169], 0, s[48:49]
	s_mov_b32 m0, s10
	ds_read_b128 v[164:167], v218 offset:49152
	ds_read_b128 v[182:185], v218 offset:50176
	ds_read_b128 v[186:189], v218 offset:51200
	ds_read_b128 v[204:207], v218 offset:52224
	ds_read_b128 v[208:211], v218 offset:53248
	ds_read_b128 v[220:223], v218 offset:54272
	ds_read_b128 v[224:227], v218 offset:55296
	ds_read_b128 v[242:245], v218 offset:56320
	global_load_lds_dwordx4 v[168:169], off
	s_add_i32 m0, s10, 0x2000
	s_add_u32 s8, s8, 0x40080
	v_lshl_add_u64 v[168:169], v[190:191], 0, s[48:49]
	s_addc_u32 s9, s9, 0
	s_add_i32 s10, s19, s29
	global_load_lds_dwordx4 v[168:169], off
	v_lshl_add_u64 v[168:169], s[8:9], 0, v[192:193]
	s_mov_b32 m0, s10
	s_nop 0
	global_load_lds_dwordx4 v[168:169], off
	v_lshl_add_u64 v[168:169], s[8:9], 0, v[174:175]
	s_add_i32 m0, s10, 0x2000
	s_nop 0
	global_load_lds_dwordx4 v[168:169], off
	v_lshl_add_u64 v[168:169], v[194:195], 0, s[48:49]
	s_mov_b32 m0, s97
	s_nop 0
	global_load_lds_dwordx4 v[168:169], off
	v_lshl_add_u64 v[168:169], v[196:197], 0, s[48:49]
	s_mov_b32 m0, s26
	s_nop 0
	global_load_lds_dwordx4 v[168:169], off
	s_waitcnt vmcnt(8)
	s_waitcnt lgkmcnt(0)
	s_barrier
	s_setprio 1
	s_waitcnt lgkmcnt(0)
	v_mfma_f32_16x16x32_bf16 v[60:63], v[132:135], v[164:167], v[60:63]
	v_mfma_f32_16x16x32_bf16 v[56:59], v[140:143], v[164:167], v[56:59]
	v_mfma_f32_16x16x32_bf16 v[44:47], v[132:135], v[186:189], v[44:47]
	v_mfma_f32_16x16x32_bf16 v[40:43], v[140:143], v[186:189], v[40:43]
	v_mfma_f32_16x16x32_bf16 v[28:31], v[132:135], v[208:211], v[28:31]
	v_mfma_f32_16x16x32_bf16 v[24:27], v[140:143], v[208:211], v[24:27]
	v_mfma_f32_16x16x32_bf16 v[12:15], v[132:135], v[224:227], v[12:15]
	v_mfma_f32_16x16x32_bf16 v[8:11], v[140:143], v[224:227], v[8:11]
	v_mfma_f32_16x16x32_bf16 v[60:63], v[136:139], v[182:185], v[60:63]
	v_mfma_f32_16x16x32_bf16 v[56:59], v[144:147], v[182:185], v[56:59]
	v_mfma_f32_16x16x32_bf16 v[44:47], v[136:139], v[204:207], v[44:47]
	v_mfma_f32_16x16x32_bf16 v[40:43], v[144:147], v[204:207], v[40:43]
	v_mfma_f32_16x16x32_bf16 v[28:31], v[136:139], v[220:223], v[28:31]
	v_mfma_f32_16x16x32_bf16 v[24:27], v[144:147], v[220:223], v[24:27]
	v_mfma_f32_16x16x32_bf16 v[12:15], v[136:139], v[242:245], v[12:15]
	v_mfma_f32_16x16x32_bf16 v[8:11], v[144:147], v[242:245], v[8:11]
	s_setprio 0
	s_setprio 1
	v_mfma_f32_16x16x32_bf16 v[52:55], v[148:151], v[164:167], v[52:55]
	v_mfma_f32_16x16x32_bf16 v[48:51], v[156:159], v[164:167], v[48:51]
	v_mfma_f32_16x16x32_bf16 v[36:39], v[148:151], v[186:189], v[36:39]
	v_mfma_f32_16x16x32_bf16 v[32:35], v[156:159], v[186:189], v[32:35]
	v_mfma_f32_16x16x32_bf16 v[20:23], v[148:151], v[208:211], v[20:23]
	v_mfma_f32_16x16x32_bf16 v[16:19], v[156:159], v[208:211], v[16:19]
	v_mfma_f32_16x16x32_bf16 v[4:7], v[148:151], v[224:227], v[4:7]
	v_mfma_f32_16x16x32_bf16 v[0:3], v[156:159], v[224:227], v[0:3]
	v_mfma_f32_16x16x32_bf16 v[52:55], v[152:155], v[182:185], v[52:55]
	v_mfma_f32_16x16x32_bf16 v[48:51], v[160:163], v[182:185], v[48:51]
	v_mfma_f32_16x16x32_bf16 v[36:39], v[152:155], v[204:207], v[36:39]
	v_mfma_f32_16x16x32_bf16 v[32:35], v[160:163], v[204:207], v[32:35]
	v_mfma_f32_16x16x32_bf16 v[20:23], v[152:155], v[220:223], v[20:23]
	v_mfma_f32_16x16x32_bf16 v[16:19], v[160:163], v[220:223], v[16:19]
	v_mfma_f32_16x16x32_bf16 v[4:7], v[152:155], v[242:245], v[4:7]
	v_mfma_f32_16x16x32_bf16 v[0:3], v[160:163], v[242:245], v[0:3]
	s_setprio 0
	s_barrier
	s_add_i32 s17, s17, 2
	s_add_u32 s2, s2, 0x100
	s_addc_u32 s3, s3, 0
	s_add_u32 s5, s5, 0x100
	s_addc_u32 s16, s16, 0
	s_cmp_gt_u32 s17, 13
	s_branch .LBB0_218

.LBB0_368:
	s_ashr_i32 s9, s8, 31
	s_lshl_b64 s[10:11], s[8:9], 19
	v_readlane_b32 s12, v252, 42
	v_readlane_b32 s13, v252, 43
	s_add_u32 s10, s12, s10
	s_addc_u32 s11, s13, s11
	s_and_b64 s[12:13], s[38:39], exec
	s_cselect_b32 s9, s11, s15
	s_cselect_b32 s41, s10, s14
	s_ashr_i32 s7, s6, 31
	s_lshl_b64 s[12:13], s[6:7], 19
	s_add_u32 s12, s20, s12
	s_addc_u32 s13, s21, s13
	s_and_b64 s[18:19], s[38:39], exec
	s_cselect_b32 s7, s13, s17
	s_cselect_b32 s42, s12, s16
	s_ashr_i32 s3, s2, 31
	s_lshl_b64 s[18:19], s[2:3], 14
	s_add_u32 s14, s14, 0x40080
	s_addc_u32 s15, s15, 0
	v_lshl_add_u64 v[140:141], v[134:135], 0, s[18:19]
	s_mov_b64 s[18:19], 0x400
	s_add_u32 s3, s16, 0x100
	v_lshl_add_u64 v[142:143], v[140:141], 0, s[18:19]
	s_addc_u32 s43, s17, 0
	s_mov_b32 s44, -2
	s_mov_b64 s[16:17], 0
	s_add_u32 s45, s14, 0xfffc0080
	s_addc_u32 s46, s15, -1
	s_and_b64 s[18:19], s[16:17], exec
	s_cselect_b32 s19, s9, s46
	s_cselect_b32 s18, s41, s45
	s_add_i32 s45, 0, 0x10000
	s_and_b64 s[16:17], s[16:17], exec
	v_add_u32_e32 v144, s45, v149
	s_cselect_b32 s17, s7, s43
	s_cselect_b32 s16, s42, s3
	s_add_i32 s50, 0, 0x14000
	ds_read_b128 v[156:159], v144
	ds_read_b128 v[160:163], v144 offset:1024
	ds_read_b128 v[164:167], v144 offset:2048
	ds_read_b128 v[168:171], v144 offset:3072
	v_add_u32_e32 v144, s50, v149
	ds_read_b128 v[172:175], v144
	ds_read_b128 v[176:179], v144 offset:1024
	ds_read_b128 v[180:183], v144 offset:2048
	ds_read_b128 v[184:187], v144 offset:3072
	v_lshl_add_u64 v[144:145], s[14:15], 0, v[136:137]
	s_add_i32 m0, s23, 0xc000
	ds_read_b128 v[188:191], v153
	ds_read_b128 v[204:207], v153 offset:1024
	ds_read_b128 v[208:211], v153 offset:2048
	ds_read_b128 v[212:215], v153 offset:3072
	ds_read_b128 v[216:219], v153 offset:4096
	ds_read_b128 v[220:223], v153 offset:5120
	ds_read_b128 v[224:227], v153 offset:6144
	ds_read_b128 v[242:245], v153 offset:7168
	global_load_lds_dwordx4 v[144:145], off
	v_lshl_add_u64 v[144:145], s[14:15], 0, v[138:139]
	s_add_i32 m0, s23, 0xe000
	s_nop 0
	global_load_lds_dwordx4 v[144:145], off
	s_waitcnt vmcnt(8)
	s_waitcnt lgkmcnt(0)
	s_barrier
	s_setprio 1
	s_waitcnt lgkmcnt(0)
	v_mfma_f32_16x16x32_bf16 v[124:127], v[156:159], v[188:191], 0
	v_mfma_f32_16x16x32_bf16 v[120:123], v[164:167], v[188:191], 0
	v_mfma_f32_16x16x32_bf16 v[108:111], v[156:159], v[208:211], 0
	v_mfma_f32_16x16x32_bf16 v[104:107], v[164:167], v[208:211], 0
	v_mfma_f32_16x16x32_bf16 v[92:95], v[156:159], v[216:219], 0
	v_mfma_f32_16x16x32_bf16 v[88:91], v[164:167], v[216:219], 0
	v_mfma_f32_16x16x32_bf16 v[76:79], v[156:159], v[224:227], 0
	v_mfma_f32_16x16x32_bf16 v[72:75], v[164:167], v[224:227], 0
	v_mfma_f32_16x16x32_bf16 v[124:127], v[160:163], v[204:207], v[124:127]
	v_mfma_f32_16x16x32_bf16 v[120:123], v[168:171], v[204:207], v[120:123]
	v_mfma_f32_16x16x32_bf16 v[108:111], v[160:163], v[212:215], v[108:111]
	v_mfma_f32_16x16x32_bf16 v[104:107], v[168:171], v[212:215], v[104:107]
	v_mfma_f32_16x16x32_bf16 v[92:95], v[160:163], v[220:223], v[92:95]
	v_mfma_f32_16x16x32_bf16 v[88:91], v[168:171], v[220:223], v[88:91]
	v_mfma_f32_16x16x32_bf16 v[76:79], v[160:163], v[242:245], v[76:79]
	v_mfma_f32_16x16x32_bf16 v[72:75], v[168:171], v[242:245], v[72:75]
	s_setprio 0
	s_setprio 1
	v_mfma_f32_16x16x32_bf16 v[116:119], v[172:175], v[188:191], 0
	v_mfma_f32_16x16x32_bf16 v[112:115], v[180:183], v[188:191], 0
	v_mfma_f32_16x16x32_bf16 v[100:103], v[172:175], v[208:211], 0
	v_mfma_f32_16x16x32_bf16 v[96:99], v[180:183], v[208:211], 0
	v_mfma_f32_16x16x32_bf16 v[84:87], v[172:175], v[216:219], 0
	v_mfma_f32_16x16x32_bf16 v[80:83], v[180:183], v[216:219], 0
	v_mfma_f32_16x16x32_bf16 v[68:71], v[172:175], v[224:227], 0
	v_mfma_f32_16x16x32_bf16 v[64:67], v[180:183], v[224:227], 0
	v_mfma_f32_16x16x32_bf16 v[116:119], v[176:179], v[204:207], v[116:119]
	v_mfma_f32_16x16x32_bf16 v[112:115], v[184:187], v[204:207], v[112:115]
	v_mfma_f32_16x16x32_bf16 v[100:103], v[176:179], v[212:215], v[100:103]
	v_mfma_f32_16x16x32_bf16 v[96:99], v[184:187], v[212:215], v[96:99]
	v_mfma_f32_16x16x32_bf16 v[84:87], v[176:179], v[220:223], v[84:87]
	v_mfma_f32_16x16x32_bf16 v[80:83], v[184:187], v[220:223], v[80:83]
	v_mfma_f32_16x16x32_bf16 v[68:71], v[176:179], v[242:245], v[68:71]
	v_mfma_f32_16x16x32_bf16 v[64:67], v[184:187], v[242:245], v[64:67]
	s_setprio 0
	s_barrier
	s_add_i32 s45, s45, s22
	v_lshl_add_u64 v[144:145], s[16:17], 0, v[192:193]
	s_mov_b32 m0, s45
	ds_read_b128 v[188:191], v153 offset:16384
	ds_read_b128 v[204:207], v153 offset:17408
	ds_read_b128 v[208:211], v153 offset:18432
	ds_read_b128 v[212:215], v153 offset:19456
	ds_read_b128 v[216:219], v153 offset:20480
	ds_read_b128 v[220:223], v153 offset:21504
	ds_read_b128 v[224:227], v153 offset:22528
	ds_read_b128 v[242:245], v153 offset:23552
	global_load_lds_dwordx4 v[144:145], off
	s_add_i32 m0, s45, 0x2000
	s_add_u32 s46, s16, 0x40000
	v_lshl_add_u64 v[194:195], s[16:17], 0, v[128:129]
	s_addc_u32 s47, s17, 0
	s_add_i32 s45, s50, s22
	global_load_lds_dwordx4 v[194:195], off
	v_lshl_add_u64 v[196:197], s[46:47], 0, v[192:193]
	s_mov_b32 m0, s45
	v_lshl_add_u64 v[198:199], s[18:19], 0, v[130:131]
	global_load_lds_dwordx4 v[196:197], off
	v_lshl_add_u64 v[196:197], s[46:47], 0, v[128:129]
	s_add_i32 m0, s45, 0x2000
	s_nop 0
	global_load_lds_dwordx4 v[196:197], off
	v_lshl_add_u64 v[196:197], s[18:19], 0, v[132:133]
	s_mov_b32 m0, s23
	s_nop 0
	global_load_lds_dwordx4 v[196:197], off
	s_mov_b32 m0, s26
	s_nop 0
	global_load_lds_dwordx4 v[198:199], off
	s_waitcnt vmcnt(8)
	s_waitcnt lgkmcnt(0)
	s_barrier
	s_setprio 1
	s_waitcnt lgkmcnt(0)
	v_mfma_f32_16x16x32_bf16 v[60:63], v[156:159], v[188:191], 0
	v_mfma_f32_16x16x32_bf16 v[56:59], v[164:167], v[188:191], 0
	v_mfma_f32_16x16x32_bf16 v[44:47], v[156:159], v[208:211], 0
	v_mfma_f32_16x16x32_bf16 v[40:43], v[164:167], v[208:211], 0
	v_mfma_f32_16x16x32_bf16 v[28:31], v[156:159], v[216:219], 0
	v_mfma_f32_16x16x32_bf16 v[24:27], v[164:167], v[216:219], 0
	v_mfma_f32_16x16x32_bf16 v[12:15], v[156:159], v[224:227], 0
	v_mfma_f32_16x16x32_bf16 v[8:11], v[164:167], v[224:227], 0
	v_mfma_f32_16x16x32_bf16 v[60:63], v[160:163], v[204:207], v[60:63]
	v_mfma_f32_16x16x32_bf16 v[56:59], v[168:171], v[204:207], v[56:59]
	v_mfma_f32_16x16x32_bf16 v[44:47], v[160:163], v[212:215], v[44:47]
	v_mfma_f32_16x16x32_bf16 v[40:43], v[168:171], v[212:215], v[40:43]
	v_mfma_f32_16x16x32_bf16 v[28:31], v[160:163], v[220:223], v[28:31]
	v_mfma_f32_16x16x32_bf16 v[24:27], v[168:171], v[220:223], v[24:27]
	v_mfma_f32_16x16x32_bf16 v[12:15], v[160:163], v[242:245], v[12:15]
	v_mfma_f32_16x16x32_bf16 v[8:11], v[168:171], v[242:245], v[8:11]
	s_setprio 0
	s_setprio 1
	v_mfma_f32_16x16x32_bf16 v[52:55], v[172:175], v[188:191], 0
	v_mfma_f32_16x16x32_bf16 v[48:51], v[180:183], v[188:191], 0
	v_mfma_f32_16x16x32_bf16 v[36:39], v[172:175], v[208:211], 0
	v_mfma_f32_16x16x32_bf16 v[32:35], v[180:183], v[208:211], 0
	v_mfma_f32_16x16x32_bf16 v[20:23], v[172:175], v[216:219], 0
	v_mfma_f32_16x16x32_bf16 v[16:19], v[180:183], v[216:219], 0
	v_mfma_f32_16x16x32_bf16 v[4:7], v[172:175], v[224:227], 0
	v_mfma_f32_16x16x32_bf16 v[0:3], v[180:183], v[224:227], 0
	v_mfma_f32_16x16x32_bf16 v[52:55], v[176:179], v[204:207], v[52:55]
	v_mfma_f32_16x16x32_bf16 v[48:51], v[184:187], v[204:207], v[48:51]
	v_mfma_f32_16x16x32_bf16 v[36:39], v[176:179], v[212:215], v[36:39]
	v_mfma_f32_16x16x32_bf16 v[32:35], v[184:187], v[212:215], v[32:35]
	v_mfma_f32_16x16x32_bf16 v[20:23], v[176:179], v[220:223], v[20:23]
	v_mfma_f32_16x16x32_bf16 v[16:19], v[184:187], v[220:223], v[16:19]
	v_mfma_f32_16x16x32_bf16 v[4:7], v[176:179], v[242:245], v[4:7]
	v_mfma_f32_16x16x32_bf16 v[0:3], v[184:187], v[242:245], v[0:3]
	s_setprio 0
	s_barrier
	s_add_i32 s45, 0, 0x18000
	v_add_u32_e32 v146, s45, v149
	s_add_i32 s46, 0, 0x1c000
	ds_read_b128 v[156:159], v146
	ds_read_b128 v[160:163], v146 offset:1024
	ds_read_b128 v[164:167], v146 offset:2048
	ds_read_b128 v[168:171], v146 offset:3072
	v_add_u32_e32 v146, s46, v149
	ds_read_b128 v[172:175], v146
	ds_read_b128 v[176:179], v146 offset:1024
	ds_read_b128 v[180:183], v146 offset:2048
	ds_read_b128 v[184:187], v146 offset:3072
	s_add_u32 s18, s18, 0x40000
	s_addc_u32 s19, s19, 0
	s_mov_b32 m0, s27
	v_lshl_add_u64 v[200:201], s[18:19], 0, v[132:133]
	ds_read_b128 v[188:191], v153 offset:32768
	ds_read_b128 v[204:207], v153 offset:33792
	ds_read_b128 v[208:211], v153 offset:34816
	ds_read_b128 v[212:215], v153 offset:35840
	ds_read_b128 v[216:219], v153 offset:36864
	ds_read_b128 v[220:223], v153 offset:37888
	ds_read_b128 v[224:227], v153 offset:38912
	ds_read_b128 v[242:245], v153 offset:39936
	global_load_lds_dwordx4 v[200:201], off
	v_lshl_add_u64 v[200:201], s[18:19], 0, v[130:131]
	s_mov_b32 m0, s28
	s_nop 0
	global_load_lds_dwordx4 v[200:201], off
	s_waitcnt vmcnt(8)
	s_waitcnt lgkmcnt(0)
	s_barrier
	s_setprio 1
	s_waitcnt lgkmcnt(0)
	v_mfma_f32_16x16x32_bf16 v[124:127], v[156:159], v[188:191], v[124:127]
	v_mfma_f32_16x16x32_bf16 v[120:123], v[164:167], v[188:191], v[120:123]
	v_mfma_f32_16x16x32_bf16 v[108:111], v[156:159], v[208:211], v[108:111]
	v_mfma_f32_16x16x32_bf16 v[104:107], v[164:167], v[208:211], v[104:107]
	v_mfma_f32_16x16x32_bf16 v[92:95], v[156:159], v[216:219], v[92:95]
	v_mfma_f32_16x16x32_bf16 v[88:91], v[164:167], v[216:219], v[88:91]
	v_mfma_f32_16x16x32_bf16 v[76:79], v[156:159], v[224:227], v[76:79]
	v_mfma_f32_16x16x32_bf16 v[72:75], v[164:167], v[224:227], v[72:75]
	v_mfma_f32_16x16x32_bf16 v[124:127], v[160:163], v[204:207], v[124:127]
	v_mfma_f32_16x16x32_bf16 v[120:123], v[168:171], v[204:207], v[120:123]
	v_mfma_f32_16x16x32_bf16 v[108:111], v[160:163], v[212:215], v[108:111]
	v_mfma_f32_16x16x32_bf16 v[104:107], v[168:171], v[212:215], v[104:107]
	v_mfma_f32_16x16x32_bf16 v[92:95], v[160:163], v[220:223], v[92:95]
	v_mfma_f32_16x16x32_bf16 v[88:91], v[168:171], v[220:223], v[88:91]
	v_mfma_f32_16x16x32_bf16 v[76:79], v[160:163], v[242:245], v[76:79]
	v_mfma_f32_16x16x32_bf16 v[72:75], v[168:171], v[242:245], v[72:75]
	s_setprio 0
	s_setprio 1
	v_mfma_f32_16x16x32_bf16 v[116:119], v[172:175], v[188:191], v[116:119]
	v_mfma_f32_16x16x32_bf16 v[112:115], v[180:183], v[188:191], v[112:115]
	v_mfma_f32_16x16x32_bf16 v[100:103], v[172:175], v[208:211], v[100:103]
	v_mfma_f32_16x16x32_bf16 v[96:99], v[180:183], v[208:211], v[96:99]
	v_mfma_f32_16x16x32_bf16 v[84:87], v[172:175], v[216:219], v[84:87]
	v_mfma_f32_16x16x32_bf16 v[80:83], v[180:183], v[216:219], v[80:83]
	v_mfma_f32_16x16x32_bf16 v[68:71], v[172:175], v[224:227], v[68:71]
	v_mfma_f32_16x16x32_bf16 v[64:67], v[180:183], v[224:227], v[64:67]
	v_mfma_f32_16x16x32_bf16 v[116:119], v[176:179], v[204:207], v[116:119]
	v_mfma_f32_16x16x32_bf16 v[112:115], v[184:187], v[204:207], v[112:115]
	v_mfma_f32_16x16x32_bf16 v[100:103], v[176:179], v[212:215], v[100:103]
	v_mfma_f32_16x16x32_bf16 v[96:99], v[184:187], v[212:215], v[96:99]
	v_mfma_f32_16x16x32_bf16 v[84:87], v[176:179], v[220:223], v[84:87]
	v_mfma_f32_16x16x32_bf16 v[80:83], v[184:187], v[220:223], v[80:83]
	v_mfma_f32_16x16x32_bf16 v[68:71], v[176:179], v[242:245], v[68:71]
	v_mfma_f32_16x16x32_bf16 v[64:67], v[184:187], v[242:245], v[64:67]
	s_setprio 0
	s_barrier
	s_add_i32 s18, s45, s22
	v_lshl_add_u64 v[144:145], v[144:145], 0, s[48:49]
	s_mov_b32 m0, s18
	ds_read_b128 v[188:191], v153 offset:49152
	ds_read_b128 v[204:207], v153 offset:50176
	ds_read_b128 v[208:211], v153 offset:51200
	ds_read_b128 v[212:215], v153 offset:52224
	ds_read_b128 v[216:219], v153 offset:53248
	ds_read_b128 v[220:223], v153 offset:54272
	ds_read_b128 v[224:227], v153 offset:55296
	ds_read_b128 v[242:245], v153 offset:56320
	global_load_lds_dwordx4 v[144:145], off
	s_add_i32 m0, s18, 0x2000
	s_add_u32 s16, s16, 0x40080
	v_lshl_add_u64 v[144:145], v[194:195], 0, s[48:49]
	s_addc_u32 s17, s17, 0
	s_add_i32 s18, s46, s22
	global_load_lds_dwordx4 v[144:145], off
	v_lshl_add_u64 v[144:145], s[16:17], 0, v[192:193]
	s_mov_b32 m0, s18
	s_nop 0
	global_load_lds_dwordx4 v[144:145], off
	v_lshl_add_u64 v[144:145], s[16:17], 0, v[128:129]
	s_add_i32 m0, s18, 0x2000
	s_nop 0
	global_load_lds_dwordx4 v[144:145], off
	v_lshl_add_u64 v[144:145], v[196:197], 0, s[48:49]
	s_mov_b32 m0, s29
	s_nop 0
	global_load_lds_dwordx4 v[144:145], off
	v_lshl_add_u64 v[144:145], v[198:199], 0, s[48:49]
	s_mov_b32 m0, s33
	s_nop 0
	global_load_lds_dwordx4 v[144:145], off
	s_waitcnt vmcnt(8)
	s_waitcnt lgkmcnt(0)
	s_barrier
	s_setprio 1
	s_waitcnt lgkmcnt(0)
	v_mfma_f32_16x16x32_bf16 v[60:63], v[156:159], v[188:191], v[60:63]
	v_mfma_f32_16x16x32_bf16 v[56:59], v[164:167], v[188:191], v[56:59]
	v_mfma_f32_16x16x32_bf16 v[44:47], v[156:159], v[208:211], v[44:47]
	v_mfma_f32_16x16x32_bf16 v[40:43], v[164:167], v[208:211], v[40:43]
	v_mfma_f32_16x16x32_bf16 v[28:31], v[156:159], v[216:219], v[28:31]
	v_mfma_f32_16x16x32_bf16 v[24:27], v[164:167], v[216:219], v[24:27]
	v_mfma_f32_16x16x32_bf16 v[12:15], v[156:159], v[224:227], v[12:15]
	v_mfma_f32_16x16x32_bf16 v[8:11], v[164:167], v[224:227], v[8:11]
	v_mfma_f32_16x16x32_bf16 v[60:63], v[160:163], v[204:207], v[60:63]
	v_mfma_f32_16x16x32_bf16 v[56:59], v[168:171], v[204:207], v[56:59]
	v_mfma_f32_16x16x32_bf16 v[44:47], v[160:163], v[212:215], v[44:47]
	v_mfma_f32_16x16x32_bf16 v[40:43], v[168:171], v[212:215], v[40:43]
	v_mfma_f32_16x16x32_bf16 v[28:31], v[160:163], v[220:223], v[28:31]
	v_mfma_f32_16x16x32_bf16 v[24:27], v[168:171], v[220:223], v[24:27]
	v_mfma_f32_16x16x32_bf16 v[12:15], v[160:163], v[242:245], v[12:15]
	v_mfma_f32_16x16x32_bf16 v[8:11], v[168:171], v[242:245], v[8:11]
	s_setprio 0
	s_setprio 1
	v_mfma_f32_16x16x32_bf16 v[52:55], v[172:175], v[188:191], v[52:55]
	v_mfma_f32_16x16x32_bf16 v[48:51], v[180:183], v[188:191], v[48:51]
	v_mfma_f32_16x16x32_bf16 v[36:39], v[172:175], v[208:211], v[36:39]
	v_mfma_f32_16x16x32_bf16 v[32:35], v[180:183], v[208:211], v[32:35]
	v_mfma_f32_16x16x32_bf16 v[20:23], v[172:175], v[216:219], v[20:23]
	v_mfma_f32_16x16x32_bf16 v[16:19], v[180:183], v[216:219], v[16:19]
	v_mfma_f32_16x16x32_bf16 v[4:7], v[172:175], v[224:227], v[4:7]
	v_mfma_f32_16x16x32_bf16 v[0:3], v[180:183], v[224:227], v[0:3]
	v_mfma_f32_16x16x32_bf16 v[52:55], v[176:179], v[204:207], v[52:55]
	v_mfma_f32_16x16x32_bf16 v[48:51], v[184:187], v[204:207], v[48:51]
	v_mfma_f32_16x16x32_bf16 v[36:39], v[176:179], v[212:215], v[36:39]
	v_mfma_f32_16x16x32_bf16 v[32:35], v[184:187], v[212:215], v[32:35]
	v_mfma_f32_16x16x32_bf16 v[20:23], v[176:179], v[220:223], v[20:23]
	v_mfma_f32_16x16x32_bf16 v[16:19], v[184:187], v[220:223], v[16:19]
	v_mfma_f32_16x16x32_bf16 v[4:7], v[176:179], v[242:245], v[4:7]
	v_mfma_f32_16x16x32_bf16 v[0:3], v[184:187], v[242:245], v[0:3]
	s_setprio 0
	s_barrier
	s_add_i32 s44, s44, 2
	s_add_u32 s14, s14, 0x100
	s_addc_u32 s15, s15, 0
	s_add_u32 s3, s3, 0x100
	s_addc_u32 s43, s43, 0
	s_cmp_gt_u32 s44, 13
	s_branch .LBB0_370

.LBB0_406:
	s_add_u32 s2, s2, 0x80
	s_addc_u32 s3, s3, 0
	s_add_u32 s34, s28, 0x100
	s_addc_u32 s35, s29, 0
	s_mov_b32 s28, 0
	s_waitcnt vmcnt(0)
	s_add_i32 s43, s28, 2
	s_add_u32 s44, s2, 0x80
	s_addc_u32 s29, s3, 0
	s_add_i32 s46, 0, 0x10000
	s_cmp_eq_u32 s68, s28
	s_cselect_b32 s29, s1, s29
	s_cselect_b32 s28, s0, s44
	s_cselect_b32 s45, s61, s35
	s_cselect_b32 s44, s60, s34
	s_add_i32 s47, 0, 0x14000
	v_add_u32_e32 v140, s46, v241
	v_add_u32_e32 v156, s47, v241
	ds_read_b128 v[128:131], v140
	ds_read_b128 v[132:135], v140 offset:1024
	ds_read_b128 v[136:139], v140 offset:2048
	ds_read_b128 v[140:143], v140 offset:3072
	ds_read_b128 v[144:147], v156
	ds_read_b128 v[148:151], v156 offset:1024
	ds_read_b128 v[152:155], v156 offset:2048
	ds_read_b128 v[156:159], v156 offset:3072
	v_lshl_add_u64 v[194:195], s[2:3], 0, v[210:211]
	s_add_i32 m0, s22, 0xc000
	ds_read_b128 v[160:163], v243
	ds_read_b128 v[164:167], v243 offset:1024
	ds_read_b128 v[168:171], v243 offset:2048
	ds_read_b128 v[172:175], v243 offset:3072
	ds_read_b128 v[176:179], v243 offset:4096
	ds_read_b128 v[180:183], v243 offset:5120
	ds_read_b128 v[184:187], v243 offset:6144
	ds_read_b128 v[188:191], v243 offset:7168
	global_load_lds_dwordx4 v[194:195], off
	v_lshl_add_u64 v[194:195], s[2:3], 0, v[212:213]
	s_add_i32 m0, s22, 0xe000
	s_nop 0
	global_load_lds_dwordx4 v[194:195], off
	s_waitcnt vmcnt(8)
	s_waitcnt lgkmcnt(0)
	s_barrier
	s_setprio 1
	s_waitcnt lgkmcnt(0)
	v_mfma_f32_16x16x32_bf16 v[124:127], v[128:131], v[160:163], 0
	v_mfma_f32_16x16x32_bf16 v[120:123], v[136:139], v[160:163], 0
	v_mfma_f32_16x16x32_bf16 v[108:111], v[128:131], v[168:171], 0
	v_mfma_f32_16x16x32_bf16 v[104:107], v[136:139], v[168:171], 0
	v_mfma_f32_16x16x32_bf16 v[92:95], v[128:131], v[176:179], 0
	v_mfma_f32_16x16x32_bf16 v[88:91], v[136:139], v[176:179], 0
	v_mfma_f32_16x16x32_bf16 v[76:79], v[128:131], v[184:187], 0
	v_mfma_f32_16x16x32_bf16 v[72:75], v[136:139], v[184:187], 0
	v_mfma_f32_16x16x32_bf16 v[124:127], v[132:135], v[164:167], v[124:127]
	v_mfma_f32_16x16x32_bf16 v[120:123], v[140:143], v[164:167], v[120:123]
	v_mfma_f32_16x16x32_bf16 v[108:111], v[132:135], v[172:175], v[108:111]
	v_mfma_f32_16x16x32_bf16 v[104:107], v[140:143], v[172:175], v[104:107]
	v_mfma_f32_16x16x32_bf16 v[92:95], v[132:135], v[180:183], v[92:95]
	v_mfma_f32_16x16x32_bf16 v[88:91], v[140:143], v[180:183], v[88:91]
	v_mfma_f32_16x16x32_bf16 v[76:79], v[132:135], v[188:191], v[76:79]
	v_mfma_f32_16x16x32_bf16 v[72:75], v[140:143], v[188:191], v[72:75]
	s_setprio 0
	s_setprio 1
	v_mfma_f32_16x16x32_bf16 v[116:119], v[144:147], v[160:163], 0
	v_mfma_f32_16x16x32_bf16 v[112:115], v[152:155], v[160:163], 0
	v_mfma_f32_16x16x32_bf16 v[100:103], v[144:147], v[168:171], 0
	v_mfma_f32_16x16x32_bf16 v[96:99], v[152:155], v[168:171], 0
	v_mfma_f32_16x16x32_bf16 v[84:87], v[144:147], v[176:179], 0
	v_mfma_f32_16x16x32_bf16 v[80:83], v[152:155], v[176:179], 0
	v_mfma_f32_16x16x32_bf16 v[68:71], v[144:147], v[184:187], 0
	v_mfma_f32_16x16x32_bf16 v[64:67], v[152:155], v[184:187], 0
	v_mfma_f32_16x16x32_bf16 v[116:119], v[148:151], v[164:167], v[116:119]
	v_mfma_f32_16x16x32_bf16 v[112:115], v[156:159], v[164:167], v[112:115]
	v_mfma_f32_16x16x32_bf16 v[100:103], v[148:151], v[172:175], v[100:103]
	v_mfma_f32_16x16x32_bf16 v[96:99], v[156:159], v[172:175], v[96:99]
	v_mfma_f32_16x16x32_bf16 v[84:87], v[148:151], v[180:183], v[84:87]
	v_mfma_f32_16x16x32_bf16 v[80:83], v[156:159], v[180:183], v[80:83]
	v_mfma_f32_16x16x32_bf16 v[68:71], v[148:151], v[188:191], v[68:71]
	v_mfma_f32_16x16x32_bf16 v[64:67], v[156:159], v[188:191], v[64:67]
	s_setprio 0
	s_barrier
	s_add_i32 s46, s46, s21
	v_lshl_add_u64 v[194:195], s[44:45], 0, v[192:193]
	s_mov_b32 m0, s46
	ds_read_b128 v[160:163], v243 offset:16384
	ds_read_b128 v[164:167], v243 offset:17408
	ds_read_b128 v[168:171], v243 offset:18432
	ds_read_b128 v[172:175], v243 offset:19456
	ds_read_b128 v[176:179], v243 offset:20480
	ds_read_b128 v[180:183], v243 offset:21504
	ds_read_b128 v[184:187], v243 offset:22528
	ds_read_b128 v[188:191], v243 offset:23552
	global_load_lds_dwordx4 v[194:195], off
	s_add_i32 m0, s46, 0x2000
	v_lshl_add_u64 v[196:197], s[44:45], 0, v[204:205]
	s_add_u32 s44, s44, s18
	s_addc_u32 s45, s45, 0
	s_add_i32 s46, s47, s21
	global_load_lds_dwordx4 v[196:197], off
	v_lshl_add_u64 v[198:199], s[44:45], 0, v[192:193]
	s_mov_b32 m0, s46
	v_lshl_add_u64 v[200:201], s[44:45], 0, v[204:205]
	global_load_lds_dwordx4 v[198:199], off
	s_add_i32 m0, s46, 0x2000
	v_lshl_add_u64 v[214:215], s[28:29], 0, v[208:209]
	global_load_lds_dwordx4 v[200:201], off
	s_mov_b32 m0, s22
	v_lshl_add_u64 v[216:217], s[28:29], 0, v[206:207]
	global_load_lds_dwordx4 v[214:215], off
	s_mov_b32 m0, s23
	s_nop 0
	global_load_lds_dwordx4 v[216:217], off
	s_waitcnt vmcnt(8)
	s_waitcnt lgkmcnt(0)
	s_barrier
	s_setprio 1
	s_waitcnt lgkmcnt(0)
	v_mfma_f32_16x16x32_bf16 v[60:63], v[128:131], v[160:163], 0
	v_mfma_f32_16x16x32_bf16 v[56:59], v[136:139], v[160:163], 0
	v_mfma_f32_16x16x32_bf16 v[44:47], v[128:131], v[168:171], 0
	v_mfma_f32_16x16x32_bf16 v[40:43], v[136:139], v[168:171], 0
	v_mfma_f32_16x16x32_bf16 v[28:31], v[128:131], v[176:179], 0
	v_mfma_f32_16x16x32_bf16 v[24:27], v[136:139], v[176:179], 0
	v_mfma_f32_16x16x32_bf16 v[12:15], v[128:131], v[184:187], 0
	v_mfma_f32_16x16x32_bf16 v[8:11], v[136:139], v[184:187], 0
	v_mfma_f32_16x16x32_bf16 v[60:63], v[132:135], v[164:167], v[60:63]
	v_mfma_f32_16x16x32_bf16 v[56:59], v[140:143], v[164:167], v[56:59]
	v_mfma_f32_16x16x32_bf16 v[44:47], v[132:135], v[172:175], v[44:47]
	v_mfma_f32_16x16x32_bf16 v[40:43], v[140:143], v[172:175], v[40:43]
	v_mfma_f32_16x16x32_bf16 v[28:31], v[132:135], v[180:183], v[28:31]
	v_mfma_f32_16x16x32_bf16 v[24:27], v[140:143], v[180:183], v[24:27]
	v_mfma_f32_16x16x32_bf16 v[12:15], v[132:135], v[188:191], v[12:15]
	v_mfma_f32_16x16x32_bf16 v[8:11], v[140:143], v[188:191], v[8:11]
	s_setprio 0
	s_setprio 1
	v_mfma_f32_16x16x32_bf16 v[52:55], v[144:147], v[160:163], 0
	v_mfma_f32_16x16x32_bf16 v[48:51], v[152:155], v[160:163], 0
	v_mfma_f32_16x16x32_bf16 v[36:39], v[144:147], v[168:171], 0
	v_mfma_f32_16x16x32_bf16 v[32:35], v[152:155], v[168:171], 0
	v_mfma_f32_16x16x32_bf16 v[20:23], v[144:147], v[176:179], 0
	v_mfma_f32_16x16x32_bf16 v[16:19], v[152:155], v[176:179], 0
	v_mfma_f32_16x16x32_bf16 v[4:7], v[144:147], v[184:187], 0
	v_mfma_f32_16x16x32_bf16 v[0:3], v[152:155], v[184:187], 0
	v_mfma_f32_16x16x32_bf16 v[52:55], v[148:151], v[164:167], v[52:55]
	v_mfma_f32_16x16x32_bf16 v[48:51], v[156:159], v[164:167], v[48:51]
	v_mfma_f32_16x16x32_bf16 v[36:39], v[148:151], v[172:175], v[36:39]
	v_mfma_f32_16x16x32_bf16 v[32:35], v[156:159], v[172:175], v[32:35]
	v_mfma_f32_16x16x32_bf16 v[20:23], v[148:151], v[180:183], v[20:23]
	v_mfma_f32_16x16x32_bf16 v[16:19], v[156:159], v[180:183], v[16:19]
	v_mfma_f32_16x16x32_bf16 v[4:7], v[148:151], v[188:191], v[4:7]
	v_mfma_f32_16x16x32_bf16 v[0:3], v[156:159], v[188:191], v[0:3]
	s_setprio 0
	s_barrier
	s_add_i32 s44, 0, 0x18000
	s_add_i32 s45, 0, 0x1c000
	v_add_u32_e32 v140, s44, v241
	v_add_u32_e32 v156, s45, v241
	ds_read_b128 v[128:131], v140
	ds_read_b128 v[132:135], v140 offset:1024
	ds_read_b128 v[136:139], v140 offset:2048
	ds_read_b128 v[140:143], v140 offset:3072
	ds_read_b128 v[144:147], v156
	ds_read_b128 v[148:151], v156 offset:1024
	ds_read_b128 v[152:155], v156 offset:2048
	ds_read_b128 v[156:159], v156 offset:3072
	s_add_u32 s28, s28, s18
	s_addc_u32 s29, s29, 0
	s_mov_b32 m0, s62
	v_lshl_add_u64 v[218:219], s[28:29], 0, v[208:209]
	ds_read_b128 v[160:163], v243 offset:32768
	ds_read_b128 v[164:167], v243 offset:33792
	ds_read_b128 v[168:171], v243 offset:34816
	ds_read_b128 v[172:175], v243 offset:35840
	ds_read_b128 v[176:179], v243 offset:36864
	ds_read_b128 v[180:183], v243 offset:37888
	ds_read_b128 v[184:187], v243 offset:38912
	ds_read_b128 v[188:191], v243 offset:39936
	global_load_lds_dwordx4 v[218:219], off
	v_lshl_add_u64 v[218:219], s[28:29], 0, v[206:207]
	s_mov_b32 m0, s63
	s_nop 0
	global_load_lds_dwordx4 v[218:219], off
	s_waitcnt vmcnt(8)
	s_waitcnt lgkmcnt(0)
	s_barrier
	s_setprio 1
	s_waitcnt lgkmcnt(0)
	v_mfma_f32_16x16x32_bf16 v[124:127], v[128:131], v[160:163], v[124:127]
	v_mfma_f32_16x16x32_bf16 v[120:123], v[136:139], v[160:163], v[120:123]
	v_mfma_f32_16x16x32_bf16 v[108:111], v[128:131], v[168:171], v[108:111]
	v_mfma_f32_16x16x32_bf16 v[104:107], v[136:139], v[168:171], v[104:107]
	v_mfma_f32_16x16x32_bf16 v[92:95], v[128:131], v[176:179], v[92:95]
	v_mfma_f32_16x16x32_bf16 v[88:91], v[136:139], v[176:179], v[88:91]
	v_mfma_f32_16x16x32_bf16 v[76:79], v[128:131], v[184:187], v[76:79]
	v_mfma_f32_16x16x32_bf16 v[72:75], v[136:139], v[184:187], v[72:75]
	v_mfma_f32_16x16x32_bf16 v[124:127], v[132:135], v[164:167], v[124:127]
	v_mfma_f32_16x16x32_bf16 v[120:123], v[140:143], v[164:167], v[120:123]
	v_mfma_f32_16x16x32_bf16 v[108:111], v[132:135], v[172:175], v[108:111]
	v_mfma_f32_16x16x32_bf16 v[104:107], v[140:143], v[172:175], v[104:107]
	v_mfma_f32_16x16x32_bf16 v[92:95], v[132:135], v[180:183], v[92:95]
	v_mfma_f32_16x16x32_bf16 v[88:91], v[140:143], v[180:183], v[88:91]
	v_mfma_f32_16x16x32_bf16 v[76:79], v[132:135], v[188:191], v[76:79]
	v_mfma_f32_16x16x32_bf16 v[72:75], v[140:143], v[188:191], v[72:75]
	s_setprio 0
	s_setprio 1
	v_mfma_f32_16x16x32_bf16 v[116:119], v[144:147], v[160:163], v[116:119]
	v_mfma_f32_16x16x32_bf16 v[112:115], v[152:155], v[160:163], v[112:115]
	v_mfma_f32_16x16x32_bf16 v[100:103], v[144:147], v[168:171], v[100:103]
	v_mfma_f32_16x16x32_bf16 v[96:99], v[152:155], v[168:171], v[96:99]
	v_mfma_f32_16x16x32_bf16 v[84:87], v[144:147], v[176:179], v[84:87]
	v_mfma_f32_16x16x32_bf16 v[80:83], v[152:155], v[176:179], v[80:83]
	v_mfma_f32_16x16x32_bf16 v[68:71], v[144:147], v[184:187], v[68:71]
	v_mfma_f32_16x16x32_bf16 v[64:67], v[152:155], v[184:187], v[64:67]
	v_mfma_f32_16x16x32_bf16 v[116:119], v[148:151], v[164:167], v[116:119]
	v_mfma_f32_16x16x32_bf16 v[112:115], v[156:159], v[164:167], v[112:115]
	v_mfma_f32_16x16x32_bf16 v[100:103], v[148:151], v[172:175], v[100:103]
	v_mfma_f32_16x16x32_bf16 v[96:99], v[156:159], v[172:175], v[96:99]
	v_mfma_f32_16x16x32_bf16 v[84:87], v[148:151], v[180:183], v[84:87]
	v_mfma_f32_16x16x32_bf16 v[80:83], v[156:159], v[180:183], v[80:83]
	v_mfma_f32_16x16x32_bf16 v[68:71], v[148:151], v[188:191], v[68:71]
	v_mfma_f32_16x16x32_bf16 v[64:67], v[156:159], v[188:191], v[64:67]
	s_setprio 0
	s_barrier
	s_add_i32 s28, s44, s21
	v_lshl_add_u64 v[194:195], v[194:195], 0, s[48:49]
	s_mov_b32 m0, s28
	ds_read_b128 v[160:163], v243 offset:49152
	ds_read_b128 v[164:167], v243 offset:50176
	ds_read_b128 v[168:171], v243 offset:51200
	ds_read_b128 v[172:175], v243 offset:52224
	ds_read_b128 v[176:179], v243 offset:53248
	ds_read_b128 v[180:183], v243 offset:54272
	ds_read_b128 v[184:187], v243 offset:55296
	ds_read_b128 v[188:191], v243 offset:56320
	global_load_lds_dwordx4 v[194:195], off
	v_lshl_add_u64 v[194:195], v[196:197], 0, s[48:49]
	s_add_i32 m0, s28, 0x2000
	s_add_i32 s28, s45, s21
	global_load_lds_dwordx4 v[194:195], off
	v_lshl_add_u64 v[194:195], v[198:199], 0, s[48:49]
	s_mov_b32 m0, s28
	s_nop 0
	global_load_lds_dwordx4 v[194:195], off
	v_lshl_add_u64 v[194:195], v[200:201], 0, s[48:49]
	s_add_i32 m0, s28, 0x2000
	s_nop 0
	global_load_lds_dwordx4 v[194:195], off
	v_lshl_add_u64 v[194:195], v[214:215], 0, s[48:49]
	s_mov_b32 m0, s66
	s_nop 0
	global_load_lds_dwordx4 v[194:195], off
	v_lshl_add_u64 v[194:195], v[216:217], 0, s[48:49]
	s_mov_b32 m0, s67
	s_nop 0
	global_load_lds_dwordx4 v[194:195], off
	s_waitcnt vmcnt(8)
	s_waitcnt lgkmcnt(0)
	s_barrier
	s_setprio 1
	s_waitcnt lgkmcnt(0)
	v_mfma_f32_16x16x32_bf16 v[60:63], v[128:131], v[160:163], v[60:63]
	v_mfma_f32_16x16x32_bf16 v[56:59], v[136:139], v[160:163], v[56:59]
	v_mfma_f32_16x16x32_bf16 v[44:47], v[128:131], v[168:171], v[44:47]
	v_mfma_f32_16x16x32_bf16 v[40:43], v[136:139], v[168:171], v[40:43]
	v_mfma_f32_16x16x32_bf16 v[28:31], v[128:131], v[176:179], v[28:31]
	v_mfma_f32_16x16x32_bf16 v[24:27], v[136:139], v[176:179], v[24:27]
	v_mfma_f32_16x16x32_bf16 v[12:15], v[128:131], v[184:187], v[12:15]
	v_mfma_f32_16x16x32_bf16 v[8:11], v[136:139], v[184:187], v[8:11]
	v_mfma_f32_16x16x32_bf16 v[60:63], v[132:135], v[164:167], v[60:63]
	v_mfma_f32_16x16x32_bf16 v[56:59], v[140:143], v[164:167], v[56:59]
	v_mfma_f32_16x16x32_bf16 v[44:47], v[132:135], v[172:175], v[44:47]
	v_mfma_f32_16x16x32_bf16 v[40:43], v[140:143], v[172:175], v[40:43]
	v_mfma_f32_16x16x32_bf16 v[28:31], v[132:135], v[180:183], v[28:31]
	v_mfma_f32_16x16x32_bf16 v[24:27], v[140:143], v[180:183], v[24:27]
	v_mfma_f32_16x16x32_bf16 v[12:15], v[132:135], v[188:191], v[12:15]
	v_mfma_f32_16x16x32_bf16 v[8:11], v[140:143], v[188:191], v[8:11]
	s_setprio 0
	s_setprio 1
	v_mfma_f32_16x16x32_bf16 v[52:55], v[144:147], v[160:163], v[52:55]
	v_mfma_f32_16x16x32_bf16 v[48:51], v[152:155], v[160:163], v[48:51]
	v_mfma_f32_16x16x32_bf16 v[36:39], v[144:147], v[168:171], v[36:39]
	v_mfma_f32_16x16x32_bf16 v[32:35], v[152:155], v[168:171], v[32:35]
	v_mfma_f32_16x16x32_bf16 v[20:23], v[144:147], v[176:179], v[20:23]
	v_mfma_f32_16x16x32_bf16 v[16:19], v[152:155], v[176:179], v[16:19]
	v_mfma_f32_16x16x32_bf16 v[4:7], v[144:147], v[184:187], v[4:7]
	v_mfma_f32_16x16x32_bf16 v[0:3], v[152:155], v[184:187], v[0:3]
	v_mfma_f32_16x16x32_bf16 v[52:55], v[148:151], v[164:167], v[52:55]
	v_mfma_f32_16x16x32_bf16 v[48:51], v[156:159], v[164:167], v[48:51]
	v_mfma_f32_16x16x32_bf16 v[36:39], v[148:151], v[172:175], v[36:39]
	v_mfma_f32_16x16x32_bf16 v[32:35], v[156:159], v[172:175], v[32:35]
	v_mfma_f32_16x16x32_bf16 v[20:23], v[148:151], v[180:183], v[20:23]
	v_mfma_f32_16x16x32_bf16 v[16:19], v[156:159], v[180:183], v[16:19]
	v_mfma_f32_16x16x32_bf16 v[4:7], v[148:151], v[188:191], v[4:7]
	v_mfma_f32_16x16x32_bf16 v[0:3], v[156:159], v[188:191], v[0:3]
	s_setprio 0
	s_barrier
	s_add_u32 s2, s2, 0x100
	s_addc_u32 s3, s3, 0
	s_add_u32 s34, s34, 0x100
	s_addc_u32 s35, s35, 0
	s_cmp_ge_u32 s43, s65
	s_mov_b32 s28, s43
